# lane-permuted (ds_bpermute) bf16 row stores in EpiProj and both SwiGLU epilogues: 4 adjacent lanes write one 64-B row segment
# baseline (speedup 1.0000x reference)
.LBB0_507:
	v_mbcnt_lo_u32_b32 v238, -1, 0
	v_mbcnt_hi_u32_b32 v238, -1, v238
	v_and_b32_e32 v236, 3, v238
	v_lshrrev_b32_e32 v238, 2, v238
	v_lshl_or_b32 v238, v236, 4, v238
	v_lshlrev_b32_e32 v238, 2, v238
	v_lshl_add_u32 v144, s18, 8, v150
	v_readlane_b32 s20, v234, 0
	v_ashrrev_i32_e32 v145, 31, v144
	v_readlane_b32 s22, v234, 2
	v_readlane_b32 s23, v234, 3
	v_pk_mul_f32 v[120:121], v[124:125], v[120:121]
	v_pk_mul_f32 v[122:123], v[126:127], v[122:123]
	v_lshl_add_u64 v[146:147], v[144:145], 3, s[22:23]
	global_load_dwordx2 v[158:159], v[146:147], off
	global_load_dwordx2 v[190:191], v[146:147], off offset:128
	global_load_dwordx2 v[192:193], v[146:147], off offset:256
	global_load_dwordx2 v[194:195], v[146:147], off offset:384
	global_load_dwordx2 v[196:197], v[146:147], off offset:1024
	global_load_dwordx2 v[198:199], v[146:147], off offset:1152
	global_load_dwordx2 v[200:201], v[146:147], off offset:1280
	global_load_dwordx2 v[202:203], v[146:147], off offset:1408
	v_pk_mul_f32 v[112:113], v[116:117], v[112:113]
	v_pk_mul_f32 v[114:115], v[118:119], v[114:115]
	v_lshl_or_b32 v148, s19, 7, v152
	v_readlane_b32 s18, v233, 8
	v_readlane_b32 s19, v233, 9
	v_ashrrev_i32_e32 v149, 31, v148
	v_pk_mul_f32 v[104:105], v[108:109], v[104:105]
	v_pk_mul_f32 v[106:107], v[110:111], v[106:107]
	v_pk_mul_f32 v[96:97], v[100:101], v[96:97]
	v_pk_mul_f32 v[98:99], v[102:103], v[98:99]
	v_pk_mul_f32 v[88:89], v[92:93], v[88:89]
	v_pk_mul_f32 v[90:91], v[94:95], v[90:91]
	v_pk_mul_f32 v[80:81], v[84:85], v[80:81]
	v_pk_mul_f32 v[82:83], v[86:87], v[82:83]
	v_pk_mul_f32 v[72:73], v[76:77], v[72:73]
	v_pk_mul_f32 v[74:75], v[78:79], v[74:75]
	v_pk_mul_f32 v[64:65], v[68:69], v[64:65]
	v_pk_mul_f32 v[66:67], v[70:71], v[66:67]
	v_pk_mul_f32 v[56:57], v[60:61], v[56:57]
	v_pk_mul_f32 v[58:59], v[62:63], v[58:59]
	v_pk_mul_f32 v[48:49], v[52:53], v[48:49]
	v_pk_mul_f32 v[50:51], v[54:55], v[50:51]
	v_pk_mul_f32 v[40:41], v[44:45], v[40:41]
	v_pk_mul_f32 v[42:43], v[46:47], v[42:43]
	v_pk_mul_f32 v[32:33], v[36:37], v[32:33]
	v_pk_mul_f32 v[34:35], v[38:39], v[34:35]
	v_pk_mul_f32 v[24:25], v[28:29], v[24:25]
	v_pk_mul_f32 v[26:27], v[30:31], v[26:27]
	v_pk_mul_f32 v[16:17], v[20:21], v[16:17]
	v_pk_mul_f32 v[18:19], v[22:23], v[18:19]
	v_pk_mul_f32 v[8:9], v[12:13], v[8:9]
	v_pk_mul_f32 v[10:11], v[14:15], v[10:11]
	v_pk_mul_f32 v[0:1], v[4:5], v[0:1]
	v_pk_mul_f32 v[2:3], v[6:7], v[2:3]
	v_readlane_b32 s21, v234, 1
	s_waitcnt vmcnt(0)
	v_ffbh_u32_e32 v145, v159
	v_min_u32_e32 v145, 32, v145
	v_lshlrev_b64 v[158:159], v145, v[158:159]
	v_min_u32_e32 v157, 1, v158
	v_or_b32_e32 v157, v159, v157
	v_cvt_f32_u32_e32 v157, v157
	v_sub_u32_e32 v145, 32, v145
	v_ldexp_f32 v145, v157, v145
	v_fmamk_f32 v145, v145, 0x2a000000, v156
	v_cmp_gt_f32_e32 vcc, s40, v145
	v_mul_f32_e32 v157, 0x4b800000, v145
	s_nop 0
	v_cndmask_b32_e32 v145, v145, v157, vcc
	v_rsq_f32_e32 v145, v145
	s_nop 0
	v_mul_f32_e32 v157, 0x45800000, v145
	v_cndmask_b32_e32 v145, v145, v157, vcc
	v_mul_f32_e32 v160, 0xbfb8aa3b, v145
	v_pk_mul_f32 v[162:163], v[124:125], v[160:161] op_sel_hi:[1,0]
	v_pk_mul_f32 v[124:125], v[126:127], v[160:161] op_sel_hi:[1,0]
	v_exp_f32_e32 v162, v162
	v_exp_f32_e32 v163, v163
	v_exp_f32_e32 v124, v124
	v_exp_f32_e32 v125, v125
	v_mul_f32_e32 v158, v145, v145
	v_pk_add_f32 v[162:163], v[162:163], 1.0 op_sel_hi:[1,0]
	v_pk_mul_f32 v[120:121], v[120:121], v[158:159] op_sel_hi:[1,0]
	v_pk_add_f32 v[124:125], v[124:125], 1.0 op_sel_hi:[1,0]
	v_rcp_f32_e32 v162, v162
	v_rcp_f32_e32 v163, v163
	v_rcp_f32_e32 v124, v124
	v_rcp_f32_e32 v125, v125
	v_pk_mul_f32 v[122:123], v[122:123], v[158:159] op_sel_hi:[1,0]
	v_pk_mul_f32 v[120:121], v[120:121], v[162:163]
	v_pk_mul_f32 v[112:113], v[112:113], v[158:159] op_sel_hi:[1,0]
	v_pk_mul_f32 v[122:123], v[122:123], v[124:125]
	v_cvt_pk_bf16_f32 v120, v120, v121
	v_cvt_pk_bf16_f32 v121, v122, v123
	v_pk_mul_f32 v[122:123], v[116:117], v[160:161] op_sel_hi:[1,0]
	v_pk_mul_f32 v[114:115], v[114:115], v[158:159] op_sel_hi:[1,0]
	v_exp_f32_e32 v122, v122
	v_exp_f32_e32 v123, v123
	s_nop 0
	v_pk_add_f32 v[122:123], v[122:123], 1.0 op_sel_hi:[1,0]
	s_nop 0
	v_rcp_f32_e32 v122, v122
	v_rcp_f32_e32 v123, v123
	s_nop 0
	v_pk_mul_f32 v[112:113], v[112:113], v[122:123]
	s_nop 0
	v_cvt_pk_bf16_f32 v122, v112, v113
	v_pk_mul_f32 v[112:113], v[118:119], v[160:161] op_sel_hi:[1,0]
	v_or_b32_e32 v119, 16, v144
	v_exp_f32_e32 v112, v112
	v_exp_f32_e32 v113, v113
	s_nop 0
	v_pk_add_f32 v[112:113], v[112:113], 1.0 op_sel_hi:[1,0]
	s_nop 0
	v_rcp_f32_e32 v112, v112
	v_rcp_f32_e32 v113, v113
	s_nop 0
	v_pk_mul_f32 v[112:113], v[114:115], v[112:113]
	s_nop 0
	v_cvt_pk_bf16_f32 v123, v112, v113
	v_mov_b64_e32 v[112:113], s[18:19]
	v_mad_i64_i32 v[116:117], s[18:19], v144, s41, v[112:113]
	v_lshlrev_b64 v[114:115], 1, v[148:149]
	v_lshl_add_u64 v[116:117], v[116:117], 0, v[114:115]
	ds_bpermute_b32 v236, v238, v116
	ds_bpermute_b32 v237, v238, v117
	ds_bpermute_b32 v120, v238, v120
	ds_bpermute_b32 v121, v238, v121
	ds_bpermute_b32 v122, v238, v122
	ds_bpermute_b32 v123, v238, v123
	s_waitcnt lgkmcnt(0)
	global_store_dwordx4 v[236:237], v[120:123], off
	s_nop 0
	s_nop 0
	v_ffbh_u32_e32 v118, v191
	v_min_u32_e32 v118, 32, v118
	v_lshlrev_b64 v[116:117], v118, v[190:191]
	v_min_u32_e32 v116, 1, v116
	v_or_b32_e32 v116, v117, v116
	v_cvt_f32_u32_e32 v116, v116
	v_sub_u32_e32 v117, 32, v118
	v_ldexp_f32 v116, v116, v117
	v_fmamk_f32 v116, v116, 0x2a000000, v156
	v_cmp_gt_f32_e32 vcc, s40, v116
	v_mul_f32_e32 v117, 0x4b800000, v116
	s_nop 0
	v_cndmask_b32_e32 v116, v116, v117, vcc
	v_rsq_f32_e32 v116, v116
	s_nop 0
	v_mul_f32_e32 v117, 0x45800000, v116
	v_cndmask_b32_e32 v117, v116, v117, vcc
	v_mul_f32_e32 v118, 0xbfb8aa3b, v117
	v_pk_mul_f32 v[120:121], v[108:109], v[118:119] op_sel_hi:[1,0]
	v_pk_mul_f32 v[108:109], v[110:111], v[118:119] op_sel_hi:[1,0]
	v_exp_f32_e32 v120, v120
	v_exp_f32_e32 v121, v121
	v_exp_f32_e32 v108, v108
	v_exp_f32_e32 v109, v109
	v_mul_f32_e32 v116, v117, v117
	v_pk_add_f32 v[120:121], v[120:121], 1.0 op_sel_hi:[1,0]
	v_pk_mul_f32 v[104:105], v[104:105], v[116:117] op_sel_hi:[1,0]
	v_pk_add_f32 v[108:109], v[108:109], 1.0 op_sel_hi:[1,0]
	v_rcp_f32_e32 v120, v120
	v_rcp_f32_e32 v121, v121
	v_rcp_f32_e32 v108, v108
	v_rcp_f32_e32 v109, v109
	v_pk_mul_f32 v[106:107], v[106:107], v[116:117] op_sel_hi:[1,0]
	v_pk_mul_f32 v[104:105], v[104:105], v[120:121]
	v_pk_mul_f32 v[96:97], v[96:97], v[116:117] op_sel_hi:[1,0]
	v_pk_mul_f32 v[106:107], v[106:107], v[108:109]
	v_cvt_pk_bf16_f32 v104, v104, v105
	v_cvt_pk_bf16_f32 v105, v106, v107
	v_pk_mul_f32 v[106:107], v[100:101], v[118:119] op_sel_hi:[1,0]
	v_pk_mul_f32 v[98:99], v[98:99], v[116:117] op_sel_hi:[1,0]
	v_exp_f32_e32 v106, v106
	v_exp_f32_e32 v107, v107
	s_nop 0
	v_pk_add_f32 v[106:107], v[106:107], 1.0 op_sel_hi:[1,0]
	s_nop 0
	v_rcp_f32_e32 v106, v106
	v_rcp_f32_e32 v107, v107
	s_nop 0
	v_pk_mul_f32 v[96:97], v[96:97], v[106:107]
	s_nop 0
	v_cvt_pk_bf16_f32 v106, v96, v97
	v_pk_mul_f32 v[96:97], v[102:103], v[118:119] op_sel_hi:[1,0]
	s_nop 0
	v_exp_f32_e32 v96, v96
	v_exp_f32_e32 v97, v97
	s_nop 0
	v_pk_add_f32 v[96:97], v[96:97], 1.0 op_sel_hi:[1,0]
	s_nop 0
	v_rcp_f32_e32 v96, v96
	v_rcp_f32_e32 v97, v97
	s_nop 0
	v_pk_mul_f32 v[96:97], v[98:99], v[96:97]
	s_nop 0
	v_cvt_pk_bf16_f32 v107, v96, v97
	v_mad_i64_i32 v[96:97], s[18:19], v119, s41, v[112:113]
	v_lshl_add_u64 v[96:97], v[96:97], 0, v[114:115]
	ds_bpermute_b32 v236, v238, v96
	ds_bpermute_b32 v237, v238, v97
	ds_bpermute_b32 v104, v238, v104
	ds_bpermute_b32 v105, v238, v105
	ds_bpermute_b32 v106, v238, v106
	ds_bpermute_b32 v107, v238, v107
	s_waitcnt lgkmcnt(0)
	global_store_dwordx4 v[236:237], v[104:107], off
	s_nop 0
	v_or_b32_e32 v99, 32, v144
	s_nop 0
	v_ffbh_u32_e32 v98, v193
	v_min_u32_e32 v98, 32, v98
	v_lshlrev_b64 v[96:97], v98, v[192:193]
	v_min_u32_e32 v96, 1, v96
	v_or_b32_e32 v96, v97, v96
	v_cvt_f32_u32_e32 v96, v96
	v_sub_u32_e32 v97, 32, v98
	v_ldexp_f32 v96, v96, v97
	v_fmamk_f32 v96, v96, 0x2a000000, v156
	v_cmp_gt_f32_e32 vcc, s40, v96
	v_mul_f32_e32 v97, 0x4b800000, v96
	s_nop 0
	v_cndmask_b32_e32 v96, v96, v97, vcc
	v_rsq_f32_e32 v96, v96
	s_nop 0
	v_mul_f32_e32 v97, 0x45800000, v96
	v_cndmask_b32_e32 v97, v96, v97, vcc
	v_mul_f32_e32 v98, 0xbfb8aa3b, v97
	v_pk_mul_f32 v[100:101], v[92:93], v[98:99] op_sel_hi:[1,0]
	v_pk_mul_f32 v[92:93], v[94:95], v[98:99] op_sel_hi:[1,0]
	v_exp_f32_e32 v100, v100
	v_exp_f32_e32 v101, v101
	v_exp_f32_e32 v92, v92
	v_exp_f32_e32 v93, v93
	v_mul_f32_e32 v96, v97, v97
	v_pk_add_f32 v[100:101], v[100:101], 1.0 op_sel_hi:[1,0]
	v_pk_mul_f32 v[88:89], v[88:89], v[96:97] op_sel_hi:[1,0]
	v_pk_add_f32 v[92:93], v[92:93], 1.0 op_sel_hi:[1,0]
	v_rcp_f32_e32 v100, v100
	v_rcp_f32_e32 v101, v101
	v_rcp_f32_e32 v92, v92
	v_rcp_f32_e32 v93, v93
	v_pk_mul_f32 v[90:91], v[90:91], v[96:97] op_sel_hi:[1,0]
	v_pk_mul_f32 v[88:89], v[88:89], v[100:101]
	v_pk_mul_f32 v[80:81], v[80:81], v[96:97] op_sel_hi:[1,0]
	v_pk_mul_f32 v[90:91], v[90:91], v[92:93]
	v_cvt_pk_bf16_f32 v88, v88, v89
	v_cvt_pk_bf16_f32 v89, v90, v91
	v_pk_mul_f32 v[90:91], v[84:85], v[98:99] op_sel_hi:[1,0]
	v_pk_mul_f32 v[82:83], v[82:83], v[96:97] op_sel_hi:[1,0]
	v_exp_f32_e32 v90, v90
	v_exp_f32_e32 v91, v91
	s_nop 0
	v_pk_add_f32 v[90:91], v[90:91], 1.0 op_sel_hi:[1,0]
	s_nop 0
	v_rcp_f32_e32 v90, v90
	v_rcp_f32_e32 v91, v91
	s_nop 0
	v_pk_mul_f32 v[80:81], v[80:81], v[90:91]
	s_nop 0
	v_cvt_pk_bf16_f32 v90, v80, v81
	v_pk_mul_f32 v[80:81], v[86:87], v[98:99] op_sel_hi:[1,0]
	s_nop 0
	v_exp_f32_e32 v80, v80
	v_exp_f32_e32 v81, v81
	s_nop 0
	v_pk_add_f32 v[80:81], v[80:81], 1.0 op_sel_hi:[1,0]
	s_nop 0
	v_rcp_f32_e32 v80, v80
	v_rcp_f32_e32 v81, v81
	s_nop 0
	v_pk_mul_f32 v[80:81], v[82:83], v[80:81]
	s_nop 0
	v_cvt_pk_bf16_f32 v91, v80, v81
	v_mad_i64_i32 v[80:81], s[18:19], v99, s41, v[112:113]
	v_lshl_add_u64 v[80:81], v[80:81], 0, v[114:115]
	ds_bpermute_b32 v236, v238, v80
	ds_bpermute_b32 v237, v238, v81
	ds_bpermute_b32 v88, v238, v88
	ds_bpermute_b32 v89, v238, v89
	ds_bpermute_b32 v90, v238, v90
	ds_bpermute_b32 v91, v238, v91
	s_waitcnt lgkmcnt(0)
	global_store_dwordx4 v[236:237], v[88:91], off
	s_nop 0
	v_or_b32_e32 v83, 48, v144
	s_nop 0
	v_ffbh_u32_e32 v82, v195
	v_min_u32_e32 v82, 32, v82
	v_lshlrev_b64 v[80:81], v82, v[194:195]
	v_min_u32_e32 v80, 1, v80
	v_or_b32_e32 v80, v81, v80
	v_cvt_f32_u32_e32 v80, v80
	v_sub_u32_e32 v81, 32, v82
	v_ldexp_f32 v80, v80, v81
	v_fmamk_f32 v80, v80, 0x2a000000, v156
	v_cmp_gt_f32_e32 vcc, s40, v80
	v_mul_f32_e32 v81, 0x4b800000, v80
	s_nop 0
	v_cndmask_b32_e32 v80, v80, v81, vcc
	v_rsq_f32_e32 v80, v80
	s_nop 0
	v_mul_f32_e32 v81, 0x45800000, v80
	v_cndmask_b32_e32 v81, v80, v81, vcc
	v_mul_f32_e32 v82, 0xbfb8aa3b, v81
	v_pk_mul_f32 v[84:85], v[76:77], v[82:83] op_sel_hi:[1,0]
	v_pk_mul_f32 v[76:77], v[78:79], v[82:83] op_sel_hi:[1,0]
	v_exp_f32_e32 v84, v84
	v_exp_f32_e32 v85, v85
	v_exp_f32_e32 v76, v76
	v_exp_f32_e32 v77, v77
	v_mul_f32_e32 v80, v81, v81
	v_pk_add_f32 v[84:85], v[84:85], 1.0 op_sel_hi:[1,0]
	v_pk_mul_f32 v[72:73], v[72:73], v[80:81] op_sel_hi:[1,0]
	v_pk_add_f32 v[76:77], v[76:77], 1.0 op_sel_hi:[1,0]
	v_rcp_f32_e32 v84, v84
	v_rcp_f32_e32 v85, v85
	v_rcp_f32_e32 v76, v76
	v_rcp_f32_e32 v77, v77
	v_pk_mul_f32 v[74:75], v[74:75], v[80:81] op_sel_hi:[1,0]
	v_pk_mul_f32 v[72:73], v[72:73], v[84:85]
	v_pk_mul_f32 v[64:65], v[64:65], v[80:81] op_sel_hi:[1,0]
	v_pk_mul_f32 v[74:75], v[74:75], v[76:77]
	v_cvt_pk_bf16_f32 v72, v72, v73
	v_cvt_pk_bf16_f32 v73, v74, v75
	v_pk_mul_f32 v[74:75], v[68:69], v[82:83] op_sel_hi:[1,0]
	v_pk_mul_f32 v[66:67], v[66:67], v[80:81] op_sel_hi:[1,0]
	v_exp_f32_e32 v74, v74
	v_exp_f32_e32 v75, v75
	s_nop 0
	v_pk_add_f32 v[74:75], v[74:75], 1.0 op_sel_hi:[1,0]
	s_nop 0
	v_rcp_f32_e32 v74, v74
	v_rcp_f32_e32 v75, v75
	s_nop 0
	v_pk_mul_f32 v[64:65], v[64:65], v[74:75]
	s_nop 0
	v_cvt_pk_bf16_f32 v74, v64, v65
	v_pk_mul_f32 v[64:65], v[70:71], v[82:83] op_sel_hi:[1,0]
	s_nop 0
	v_exp_f32_e32 v64, v64
	v_exp_f32_e32 v65, v65
	s_nop 0
	v_pk_add_f32 v[64:65], v[64:65], 1.0 op_sel_hi:[1,0]
	s_nop 0
	v_rcp_f32_e32 v64, v64
	v_rcp_f32_e32 v65, v65
	s_nop 0
	v_pk_mul_f32 v[64:65], v[66:67], v[64:65]
	s_nop 0
	v_cvt_pk_bf16_f32 v75, v64, v65
	v_mad_i64_i32 v[64:65], s[18:19], v83, s41, v[112:113]
	v_lshl_add_u64 v[64:65], v[64:65], 0, v[114:115]
	ds_bpermute_b32 v236, v238, v64
	ds_bpermute_b32 v237, v238, v65
	ds_bpermute_b32 v72, v238, v72
	ds_bpermute_b32 v73, v238, v73
	ds_bpermute_b32 v74, v238, v74
	ds_bpermute_b32 v75, v238, v75
	s_waitcnt lgkmcnt(0)
	global_store_dwordx4 v[236:237], v[72:75], off
	s_nop 0
	v_add_u32_e32 v67, 0x80, v144
	s_nop 0
	v_ffbh_u32_e32 v66, v197
	v_min_u32_e32 v66, 32, v66
	v_lshlrev_b64 v[64:65], v66, v[196:197]
	v_min_u32_e32 v64, 1, v64
	v_or_b32_e32 v64, v65, v64
	v_cvt_f32_u32_e32 v64, v64
	v_sub_u32_e32 v65, 32, v66
	v_ldexp_f32 v64, v64, v65
	v_fmamk_f32 v64, v64, 0x2a000000, v156
	v_cmp_gt_f32_e32 vcc, s40, v64
	v_mul_f32_e32 v65, 0x4b800000, v64
	s_nop 0
	v_cndmask_b32_e32 v64, v64, v65, vcc
	v_rsq_f32_e32 v64, v64
	s_nop 0
	v_mul_f32_e32 v65, 0x45800000, v64
	v_cndmask_b32_e32 v65, v64, v65, vcc
	v_mul_f32_e32 v66, 0xbfb8aa3b, v65
	v_pk_mul_f32 v[68:69], v[60:61], v[66:67] op_sel_hi:[1,0]
	v_pk_mul_f32 v[60:61], v[62:63], v[66:67] op_sel_hi:[1,0]
	v_exp_f32_e32 v68, v68
	v_exp_f32_e32 v69, v69
	v_exp_f32_e32 v60, v60
	v_exp_f32_e32 v61, v61
	v_mul_f32_e32 v64, v65, v65
	v_pk_add_f32 v[68:69], v[68:69], 1.0 op_sel_hi:[1,0]
	v_pk_mul_f32 v[56:57], v[56:57], v[64:65] op_sel_hi:[1,0]
	v_pk_add_f32 v[60:61], v[60:61], 1.0 op_sel_hi:[1,0]
	v_rcp_f32_e32 v68, v68
	v_rcp_f32_e32 v69, v69
	v_rcp_f32_e32 v60, v60
	v_rcp_f32_e32 v61, v61
	v_pk_mul_f32 v[58:59], v[58:59], v[64:65] op_sel_hi:[1,0]
	v_pk_mul_f32 v[56:57], v[56:57], v[68:69]
	v_pk_mul_f32 v[48:49], v[48:49], v[64:65] op_sel_hi:[1,0]
	v_pk_mul_f32 v[58:59], v[58:59], v[60:61]
	v_cvt_pk_bf16_f32 v56, v56, v57
	v_cvt_pk_bf16_f32 v57, v58, v59
	v_pk_mul_f32 v[58:59], v[52:53], v[66:67] op_sel_hi:[1,0]
	v_pk_mul_f32 v[50:51], v[50:51], v[64:65] op_sel_hi:[1,0]
	v_exp_f32_e32 v58, v58
	v_exp_f32_e32 v59, v59
	s_nop 0
	v_pk_add_f32 v[58:59], v[58:59], 1.0 op_sel_hi:[1,0]
	s_nop 0
	v_rcp_f32_e32 v58, v58
	v_rcp_f32_e32 v59, v59
	s_nop 0
	v_pk_mul_f32 v[48:49], v[48:49], v[58:59]
	s_nop 0
	v_cvt_pk_bf16_f32 v58, v48, v49
	v_pk_mul_f32 v[48:49], v[54:55], v[66:67] op_sel_hi:[1,0]
	s_nop 0
	v_exp_f32_e32 v48, v48
	v_exp_f32_e32 v49, v49
	s_nop 0
	v_pk_add_f32 v[48:49], v[48:49], 1.0 op_sel_hi:[1,0]
	s_nop 0
	v_rcp_f32_e32 v48, v48
	v_rcp_f32_e32 v49, v49
	s_nop 0
	v_pk_mul_f32 v[48:49], v[50:51], v[48:49]
	s_nop 0
	v_cvt_pk_bf16_f32 v59, v48, v49
	v_mad_i64_i32 v[48:49], s[18:19], v67, s41, v[112:113]
	v_lshl_add_u64 v[48:49], v[48:49], 0, v[114:115]
	ds_bpermute_b32 v236, v238, v48
	ds_bpermute_b32 v237, v238, v49
	ds_bpermute_b32 v56, v238, v56
	ds_bpermute_b32 v57, v238, v57
	ds_bpermute_b32 v58, v238, v58
	ds_bpermute_b32 v59, v238, v59
	s_waitcnt lgkmcnt(0)
	global_store_dwordx4 v[236:237], v[56:59], off
	s_nop 0
	v_add_u32_e32 v51, 0x90, v144
	s_nop 0
	v_ffbh_u32_e32 v50, v199
	v_min_u32_e32 v50, 32, v50
	v_lshlrev_b64 v[48:49], v50, v[198:199]
	v_min_u32_e32 v48, 1, v48
	v_or_b32_e32 v48, v49, v48
	v_cvt_f32_u32_e32 v48, v48
	v_sub_u32_e32 v49, 32, v50
	v_ldexp_f32 v48, v48, v49
	v_fmamk_f32 v48, v48, 0x2a000000, v156
	v_cmp_gt_f32_e32 vcc, s40, v48
	v_mul_f32_e32 v49, 0x4b800000, v48
	s_nop 0
	v_cndmask_b32_e32 v48, v48, v49, vcc
	v_rsq_f32_e32 v48, v48
	s_nop 0
	v_mul_f32_e32 v49, 0x45800000, v48
	v_cndmask_b32_e32 v49, v48, v49, vcc
	v_mul_f32_e32 v50, 0xbfb8aa3b, v49
	v_pk_mul_f32 v[52:53], v[44:45], v[50:51] op_sel_hi:[1,0]
	v_pk_mul_f32 v[44:45], v[46:47], v[50:51] op_sel_hi:[1,0]
	v_exp_f32_e32 v52, v52
	v_exp_f32_e32 v53, v53
	v_exp_f32_e32 v44, v44
	v_exp_f32_e32 v45, v45
	v_mul_f32_e32 v48, v49, v49
	v_pk_add_f32 v[52:53], v[52:53], 1.0 op_sel_hi:[1,0]
	v_pk_mul_f32 v[40:41], v[40:41], v[48:49] op_sel_hi:[1,0]
	v_pk_add_f32 v[44:45], v[44:45], 1.0 op_sel_hi:[1,0]
	v_rcp_f32_e32 v52, v52
	v_rcp_f32_e32 v53, v53
	v_rcp_f32_e32 v44, v44
	v_rcp_f32_e32 v45, v45
	v_pk_mul_f32 v[42:43], v[42:43], v[48:49] op_sel_hi:[1,0]
	v_pk_mul_f32 v[40:41], v[40:41], v[52:53]
	v_pk_mul_f32 v[32:33], v[32:33], v[48:49] op_sel_hi:[1,0]
	v_pk_mul_f32 v[42:43], v[42:43], v[44:45]
	v_cvt_pk_bf16_f32 v40, v40, v41
	v_cvt_pk_bf16_f32 v41, v42, v43
	v_pk_mul_f32 v[42:43], v[36:37], v[50:51] op_sel_hi:[1,0]
	v_pk_mul_f32 v[34:35], v[34:35], v[48:49] op_sel_hi:[1,0]
	v_exp_f32_e32 v42, v42
	v_exp_f32_e32 v43, v43
	s_nop 0
	v_pk_add_f32 v[42:43], v[42:43], 1.0 op_sel_hi:[1,0]
	s_nop 0
	v_rcp_f32_e32 v42, v42
	v_rcp_f32_e32 v43, v43
	s_nop 0
	v_pk_mul_f32 v[32:33], v[32:33], v[42:43]
	s_nop 0
	v_cvt_pk_bf16_f32 v42, v32, v33
	v_pk_mul_f32 v[32:33], v[38:39], v[50:51] op_sel_hi:[1,0]
	s_nop 0
	v_exp_f32_e32 v32, v32
	v_exp_f32_e32 v33, v33
	s_nop 0
	v_pk_add_f32 v[32:33], v[32:33], 1.0 op_sel_hi:[1,0]
	s_nop 0
	v_rcp_f32_e32 v32, v32
	v_rcp_f32_e32 v33, v33
	s_nop 0
	v_pk_mul_f32 v[32:33], v[34:35], v[32:33]
	s_nop 0
	v_cvt_pk_bf16_f32 v43, v32, v33
	v_mad_i64_i32 v[32:33], s[18:19], v51, s41, v[112:113]
	v_lshl_add_u64 v[32:33], v[32:33], 0, v[114:115]
	ds_bpermute_b32 v236, v238, v32
	ds_bpermute_b32 v237, v238, v33
	ds_bpermute_b32 v40, v238, v40
	ds_bpermute_b32 v41, v238, v41
	ds_bpermute_b32 v42, v238, v42
	ds_bpermute_b32 v43, v238, v43
	s_waitcnt lgkmcnt(0)
	global_store_dwordx4 v[236:237], v[40:43], off
	s_nop 0
	v_add_u32_e32 v35, 0xa0, v144
	s_nop 0
	v_ffbh_u32_e32 v34, v201
	v_min_u32_e32 v34, 32, v34
	v_lshlrev_b64 v[32:33], v34, v[200:201]
	v_min_u32_e32 v32, 1, v32
	v_or_b32_e32 v32, v33, v32
	v_cvt_f32_u32_e32 v32, v32
	v_sub_u32_e32 v33, 32, v34
	v_ldexp_f32 v32, v32, v33
	v_fmamk_f32 v32, v32, 0x2a000000, v156
	v_cmp_gt_f32_e32 vcc, s40, v32
	v_mul_f32_e32 v33, 0x4b800000, v32
	s_nop 0
	v_cndmask_b32_e32 v32, v32, v33, vcc
	v_rsq_f32_e32 v32, v32
	s_nop 0
	v_mul_f32_e32 v33, 0x45800000, v32
	v_cndmask_b32_e32 v33, v32, v33, vcc
	v_mul_f32_e32 v34, 0xbfb8aa3b, v33
	v_pk_mul_f32 v[36:37], v[28:29], v[34:35] op_sel_hi:[1,0]
	v_pk_mul_f32 v[28:29], v[30:31], v[34:35] op_sel_hi:[1,0]
	v_exp_f32_e32 v36, v36
	v_exp_f32_e32 v37, v37
	v_exp_f32_e32 v28, v28
	v_exp_f32_e32 v29, v29
	v_mul_f32_e32 v32, v33, v33
	v_pk_add_f32 v[36:37], v[36:37], 1.0 op_sel_hi:[1,0]
	v_pk_mul_f32 v[24:25], v[24:25], v[32:33] op_sel_hi:[1,0]
	v_pk_add_f32 v[28:29], v[28:29], 1.0 op_sel_hi:[1,0]
	v_rcp_f32_e32 v36, v36
	v_rcp_f32_e32 v37, v37
	v_rcp_f32_e32 v28, v28
	v_rcp_f32_e32 v29, v29
	v_pk_mul_f32 v[26:27], v[26:27], v[32:33] op_sel_hi:[1,0]
	v_pk_mul_f32 v[24:25], v[24:25], v[36:37]
	v_pk_mul_f32 v[16:17], v[16:17], v[32:33] op_sel_hi:[1,0]
	v_pk_mul_f32 v[26:27], v[26:27], v[28:29]
	v_cvt_pk_bf16_f32 v24, v24, v25
	v_cvt_pk_bf16_f32 v25, v26, v27
	v_pk_mul_f32 v[26:27], v[20:21], v[34:35] op_sel_hi:[1,0]
	v_pk_mul_f32 v[18:19], v[18:19], v[32:33] op_sel_hi:[1,0]
	v_exp_f32_e32 v26, v26
	v_exp_f32_e32 v27, v27
	s_nop 0
	v_pk_add_f32 v[26:27], v[26:27], 1.0 op_sel_hi:[1,0]
	s_nop 0
	v_rcp_f32_e32 v26, v26
	v_rcp_f32_e32 v27, v27
	s_nop 0
	v_pk_mul_f32 v[16:17], v[16:17], v[26:27]
	s_nop 0
	v_cvt_pk_bf16_f32 v26, v16, v17
	v_pk_mul_f32 v[16:17], v[22:23], v[34:35] op_sel_hi:[1,0]
	s_nop 0
	v_exp_f32_e32 v16, v16
	v_exp_f32_e32 v17, v17
	s_nop 0
	v_pk_add_f32 v[16:17], v[16:17], 1.0 op_sel_hi:[1,0]
	s_nop 0
	v_rcp_f32_e32 v16, v16
	v_rcp_f32_e32 v17, v17
	s_nop 0
	v_pk_mul_f32 v[16:17], v[18:19], v[16:17]
	s_nop 0
	v_cvt_pk_bf16_f32 v27, v16, v17
	v_mad_i64_i32 v[16:17], s[18:19], v35, s41, v[112:113]
	v_lshl_add_u64 v[16:17], v[16:17], 0, v[114:115]
	ds_bpermute_b32 v236, v238, v16
	ds_bpermute_b32 v237, v238, v17
	ds_bpermute_b32 v24, v238, v24
	ds_bpermute_b32 v25, v238, v25
	ds_bpermute_b32 v26, v238, v26
	ds_bpermute_b32 v27, v238, v27
	s_waitcnt lgkmcnt(0)
	global_store_dwordx4 v[236:237], v[24:27], off
	s_nop 0
	v_add_u32_e32 v19, 0xb0, v144
	s_nop 0
	v_ffbh_u32_e32 v18, v203
	v_min_u32_e32 v18, 32, v18
	v_lshlrev_b64 v[16:17], v18, v[202:203]
	v_min_u32_e32 v16, 1, v16
	v_or_b32_e32 v16, v17, v16
	v_cvt_f32_u32_e32 v16, v16
	v_sub_u32_e32 v17, 32, v18
	v_ldexp_f32 v16, v16, v17
	v_fmamk_f32 v16, v16, 0x2a000000, v156
	v_cmp_gt_f32_e32 vcc, s40, v16
	v_mul_f32_e32 v17, 0x4b800000, v16
	s_nop 0
	v_cndmask_b32_e32 v16, v16, v17, vcc
	v_rsq_f32_e32 v16, v16
	s_nop 0
	v_mul_f32_e32 v17, 0x45800000, v16
	v_cndmask_b32_e32 v17, v16, v17, vcc
	v_mul_f32_e32 v18, 0xbfb8aa3b, v17
	v_pk_mul_f32 v[20:21], v[12:13], v[18:19] op_sel_hi:[1,0]
	v_pk_mul_f32 v[12:13], v[14:15], v[18:19] op_sel_hi:[1,0]
	v_exp_f32_e32 v20, v20
	v_exp_f32_e32 v21, v21
	v_exp_f32_e32 v12, v12
	v_exp_f32_e32 v13, v13
	v_mul_f32_e32 v16, v17, v17
	v_pk_add_f32 v[20:21], v[20:21], 1.0 op_sel_hi:[1,0]
	v_pk_mul_f32 v[8:9], v[8:9], v[16:17] op_sel_hi:[1,0]
	v_pk_add_f32 v[12:13], v[12:13], 1.0 op_sel_hi:[1,0]
	v_rcp_f32_e32 v20, v20
	v_rcp_f32_e32 v21, v21
	v_rcp_f32_e32 v12, v12
	v_rcp_f32_e32 v13, v13
	v_pk_mul_f32 v[10:11], v[10:11], v[16:17] op_sel_hi:[1,0]
	v_pk_mul_f32 v[8:9], v[8:9], v[20:21]
	v_pk_mul_f32 v[0:1], v[0:1], v[16:17] op_sel_hi:[1,0]
	v_pk_mul_f32 v[10:11], v[10:11], v[12:13]
	v_cvt_pk_bf16_f32 v8, v8, v9
	v_cvt_pk_bf16_f32 v9, v10, v11
	v_pk_mul_f32 v[10:11], v[4:5], v[18:19] op_sel_hi:[1,0]
	v_pk_mul_f32 v[2:3], v[2:3], v[16:17] op_sel_hi:[1,0]
	v_exp_f32_e32 v10, v10
	v_exp_f32_e32 v11, v11
	s_andn2_b64 vcc, exec, s[0:1]
	v_pk_add_f32 v[10:11], v[10:11], 1.0 op_sel_hi:[1,0]
	s_nop 0
	v_rcp_f32_e32 v10, v10
	v_rcp_f32_e32 v11, v11
	s_nop 0
	v_pk_mul_f32 v[0:1], v[0:1], v[10:11]
	s_nop 0
	v_cvt_pk_bf16_f32 v10, v0, v1
	v_pk_mul_f32 v[0:1], v[6:7], v[18:19] op_sel_hi:[1,0]
	s_nop 0
	v_exp_f32_e32 v0, v0
	v_exp_f32_e32 v1, v1
	s_nop 0
	v_pk_add_f32 v[0:1], v[0:1], 1.0 op_sel_hi:[1,0]
	s_nop 0
	v_rcp_f32_e32 v0, v0
	v_rcp_f32_e32 v1, v1
	s_nop 0
	v_pk_mul_f32 v[0:1], v[2:3], v[0:1]
	s_nop 0
	v_cvt_pk_bf16_f32 v11, v0, v1
	v_mad_i64_i32 v[0:1], s[18:19], v19, s41, v[112:113]
	v_lshl_add_u64 v[0:1], v[0:1], 0, v[114:115]
	s_mov_b64 s[18:19], -1
	ds_bpermute_b32 v236, v238, v0
	ds_bpermute_b32 v237, v238, v1
	ds_bpermute_b32 v8, v238, v8
	ds_bpermute_b32 v9, v238, v9
	ds_bpermute_b32 v10, v238, v10
	ds_bpermute_b32 v11, v238, v11
	s_waitcnt lgkmcnt(0)
	global_store_dwordx4 v[236:237], v[8:11], off
	s_cbranch_vccnz .LBB0_496
	s_andn2_b64 vcc, exec, s[4:5]
	s_cbranch_vccnz .LBB0_495
	s_barrier
	s_branch .LBB0_495

.LBB0_2314:
	v_mbcnt_lo_u32_b32 v238, -1, 0
	v_mbcnt_hi_u32_b32 v238, -1, v238
	v_and_b32_e32 v236, 3, v238
	v_lshrrev_b32_e32 v238, 2, v238
	v_lshl_or_b32 v238, v236, 4, v238
	v_lshlrev_b32_e32 v238, 2, v238
	v_lshl_add_u32 v144, s0, 8, v152
	v_ashrrev_i32_e32 v145, 31, v144
	v_lshl_add_u64 v[146:147], v[144:145], 3, s[4:5]
	global_load_dwordx2 v[160:161], v[146:147], off
	global_load_dwordx2 v[190:191], v[146:147], off offset:128
	global_load_dwordx2 v[192:193], v[146:147], off offset:256
	global_load_dwordx2 v[194:195], v[146:147], off offset:384
	global_load_dwordx2 v[196:197], v[146:147], off offset:1024
	global_load_dwordx2 v[198:199], v[146:147], off offset:1152
	global_load_dwordx2 v[200:201], v[146:147], off offset:1280
	global_load_dwordx2 v[202:203], v[146:147], off offset:1408
	v_pk_mul_f32 v[164:165], v[114:115], v[122:123]
	v_pk_mul_f32 v[126:127], v[118:119], v[126:127]
	v_pk_mul_f32 v[124:125], v[116:117], v[124:125]
	v_pk_mul_f32 v[166:167], v[112:113], v[120:121]
	v_lshl_or_b32 v162, s1, 7, v154
	v_readlane_b32 s0, v233, 8
	v_readlane_b32 s1, v233, 9
	v_ashrrev_i32_e32 v163, 31, v162
	v_pk_mul_f32 v[110:111], v[102:103], v[110:111]
	v_mov_b64_e32 v[120:121], s[0:1]
	v_mad_i64_i32 v[168:169], s[0:1], v144, s43, v[120:121]
	v_pk_mul_f32 v[108:109], v[100:101], v[108:109]
	v_pk_mul_f32 v[106:107], v[98:99], v[106:107]
	v_pk_mul_f32 v[104:105], v[96:97], v[104:105]
	v_pk_mul_f32 v[94:95], v[86:87], v[94:95]
	v_pk_mul_f32 v[92:93], v[84:85], v[92:93]
	v_pk_mul_f32 v[90:91], v[82:83], v[90:91]
	v_pk_mul_f32 v[88:89], v[80:81], v[88:89]
	v_pk_mul_f32 v[78:79], v[74:75], v[78:79]
	v_pk_mul_f32 v[76:77], v[72:73], v[76:77]
	v_pk_mul_f32 v[70:71], v[66:67], v[70:71]
	v_pk_mul_f32 v[68:69], v[64:65], v[68:69]
	v_pk_mul_f32 v[62:63], v[54:55], v[62:63]
	v_pk_mul_f32 v[60:61], v[52:53], v[60:61]
	v_pk_mul_f32 v[58:59], v[50:51], v[58:59]
	v_pk_mul_f32 v[56:57], v[48:49], v[56:57]
	v_pk_mul_f32 v[46:47], v[38:39], v[46:47]
	v_pk_mul_f32 v[44:45], v[36:37], v[44:45]
	v_pk_mul_f32 v[42:43], v[34:35], v[42:43]
	v_pk_mul_f32 v[40:41], v[32:33], v[40:41]
	v_pk_mul_f32 v[30:31], v[22:23], v[30:31]
	v_pk_mul_f32 v[28:29], v[20:21], v[28:29]
	v_pk_mul_f32 v[26:27], v[18:19], v[26:27]
	v_pk_mul_f32 v[24:25], v[16:17], v[24:25]
	v_pk_mul_f32 v[14:15], v[6:7], v[14:15]
	v_pk_mul_f32 v[12:13], v[4:5], v[12:13]
	v_pk_mul_f32 v[10:11], v[2:3], v[10:11]
	v_pk_mul_f32 v[8:9], v[0:1], v[8:9]
	s_waitcnt vmcnt(0)
	v_ffbh_u32_e32 v122, v161
	v_min_u32_e32 v145, 32, v122
	v_lshlrev_b64 v[122:123], v145, v[160:161]
	v_min_u32_e32 v122, 1, v122
	v_or_b32_e32 v122, v123, v122
	v_cvt_f32_u32_e32 v159, v122
	v_sub_u32_e32 v145, 32, v145
	v_or_b32_e32 v160, 16, v144
	v_lshlrev_b64 v[122:123], 1, v[162:163]
	v_ldexp_f32 v145, v159, v145
	v_fmamk_f32 v145, v145, 0x2a000000, v158
	v_mul_f32_e32 v159, 0x4b800000, v145
	v_cmp_gt_f32_e32 vcc, s42, v145
	v_ashrrev_i32_e32 v161, 31, v160
	v_lshl_add_u64 v[162:163], v[168:169], 0, v[122:123]
	v_cndmask_b32_e32 v145, v145, v159, vcc
	v_rsq_f32_e32 v145, v145
	v_lshl_add_u64 v[168:169], v[160:161], 3, s[4:5]
	v_mul_f32_e32 v159, 0x45800000, v145
	v_cndmask_b32_e32 v145, v145, v159, vcc
	v_mul_f32_e32 v172, 0xbfb8aa3b, v145
	v_pk_mul_f32 v[116:117], v[116:117], v[172:173] op_sel_hi:[1,0]
	v_pk_mul_f32 v[118:119], v[118:119], v[172:173] op_sel_hi:[1,0]
	v_pk_mul_f32 v[112:113], v[112:113], v[172:173] op_sel_hi:[1,0]
	v_pk_mul_f32 v[114:115], v[114:115], v[172:173] op_sel_hi:[1,0]
	v_exp_f32_e32 v116, v116
	v_exp_f32_e32 v117, v117
	v_exp_f32_e32 v118, v118
	v_exp_f32_e32 v119, v119
	v_exp_f32_e32 v112, v112
	v_exp_f32_e32 v113, v113
	v_exp_f32_e32 v114, v114
	v_exp_f32_e32 v115, v115
	v_pk_add_f32 v[116:117], v[116:117], 1.0 op_sel_hi:[1,0]
	v_pk_add_f32 v[118:119], v[118:119], 1.0 op_sel_hi:[1,0]
	v_pk_add_f32 v[112:113], v[112:113], 1.0 op_sel_hi:[1,0]
	v_pk_add_f32 v[114:115], v[114:115], 1.0 op_sel_hi:[1,0]
	v_rcp_f32_e32 v116, v116
	v_rcp_f32_e32 v117, v117
	v_rcp_f32_e32 v118, v118
	v_rcp_f32_e32 v119, v119
	v_rcp_f32_e32 v112, v112
	v_rcp_f32_e32 v113, v113
	v_rcp_f32_e32 v114, v114
	v_rcp_f32_e32 v115, v115
	v_mul_f32_e32 v170, v145, v145
	v_pk_mul_f32 v[124:125], v[124:125], v[170:171] op_sel_hi:[1,0]
	v_pk_mul_f32 v[126:127], v[126:127], v[170:171] op_sel_hi:[1,0]
	v_pk_mul_f32 v[166:167], v[166:167], v[170:171] op_sel_hi:[1,0]
	v_pk_mul_f32 v[164:165], v[164:165], v[170:171] op_sel_hi:[1,0]
	v_pk_mul_f32 v[116:117], v[124:125], v[116:117]
	v_pk_mul_f32 v[118:119], v[126:127], v[118:119]
	v_pk_mul_f32 v[124:125], v[166:167], v[112:113]
	v_pk_mul_f32 v[126:127], v[164:165], v[114:115]
	v_cvt_pk_bf16_f32 v112, v116, v117
	v_cvt_pk_bf16_f32 v113, v118, v119
	v_cvt_pk_bf16_f32 v114, v124, v125
	v_cvt_pk_bf16_f32 v115, v126, v127
	ds_bpermute_b32 v236, v238, v162
	ds_bpermute_b32 v237, v238, v163
	ds_bpermute_b32 v112, v238, v112
	ds_bpermute_b32 v113, v238, v113
	ds_bpermute_b32 v114, v238, v114
	ds_bpermute_b32 v115, v238, v115
	s_waitcnt lgkmcnt(0)
	global_store_dwordx4 v[236:237], v[112:115], off
	s_nop 0
	s_nop 0
	v_or_b32_e32 v114, 32, v144
	s_nop 0
	v_ffbh_u32_e32 v115, v191
	v_min_u32_e32 v115, 32, v115
	v_lshlrev_b64 v[112:113], v115, v[190:191]
	v_min_u32_e32 v112, 1, v112
	v_or_b32_e32 v112, v113, v112
	v_cvt_f32_u32_e32 v116, v112
	v_sub_u32_e32 v115, 32, v115
	v_mad_i64_i32 v[112:113], s[0:1], v160, s43, v[120:121]
	v_ldexp_f32 v115, v116, v115
	v_fmamk_f32 v115, v115, 0x2a000000, v158
	v_mul_f32_e32 v116, 0x4b800000, v115
	v_cmp_gt_f32_e32 vcc, s42, v115
	v_lshl_add_u64 v[112:113], v[112:113], 0, v[122:123]
	s_nop 0
	v_cndmask_b32_e32 v115, v115, v116, vcc
	v_rsq_f32_e32 v118, v115
	v_ashrrev_i32_e32 v115, 31, v114
	v_lshl_add_u64 v[116:117], v[114:115], 3, s[4:5]
	v_mul_f32_e32 v115, 0x45800000, v118
	v_cndmask_b32_e32 v115, v118, v115, vcc
	v_mul_f32_e32 v124, 0xbfb8aa3b, v115
	v_pk_mul_f32 v[100:101], v[100:101], v[124:125] op_sel_hi:[1,0]
	v_pk_mul_f32 v[102:103], v[102:103], v[124:125] op_sel_hi:[1,0]
	v_pk_mul_f32 v[96:97], v[96:97], v[124:125] op_sel_hi:[1,0]
	v_pk_mul_f32 v[98:99], v[98:99], v[124:125] op_sel_hi:[1,0]
	v_exp_f32_e32 v100, v100
	v_exp_f32_e32 v101, v101
	v_exp_f32_e32 v102, v102
	v_exp_f32_e32 v103, v103
	v_exp_f32_e32 v96, v96
	v_exp_f32_e32 v97, v97
	v_exp_f32_e32 v98, v98
	v_exp_f32_e32 v99, v99
	v_pk_add_f32 v[100:101], v[100:101], 1.0 op_sel_hi:[1,0]
	v_pk_add_f32 v[102:103], v[102:103], 1.0 op_sel_hi:[1,0]
	v_pk_add_f32 v[96:97], v[96:97], 1.0 op_sel_hi:[1,0]
	v_pk_add_f32 v[98:99], v[98:99], 1.0 op_sel_hi:[1,0]
	v_rcp_f32_e32 v100, v100
	v_rcp_f32_e32 v101, v101
	v_rcp_f32_e32 v102, v102
	v_rcp_f32_e32 v103, v103
	v_rcp_f32_e32 v96, v96
	v_rcp_f32_e32 v97, v97
	v_rcp_f32_e32 v98, v98
	v_rcp_f32_e32 v99, v99
	v_mul_f32_e32 v118, v115, v115
	v_pk_mul_f32 v[108:109], v[108:109], v[118:119] op_sel_hi:[1,0]
	v_pk_mul_f32 v[110:111], v[110:111], v[118:119] op_sel_hi:[1,0]
	v_pk_mul_f32 v[104:105], v[104:105], v[118:119] op_sel_hi:[1,0]
	v_pk_mul_f32 v[106:107], v[106:107], v[118:119] op_sel_hi:[1,0]
	v_pk_mul_f32 v[100:101], v[108:109], v[100:101]
	v_pk_mul_f32 v[102:103], v[110:111], v[102:103]
	v_pk_mul_f32 v[104:105], v[104:105], v[96:97]
	v_pk_mul_f32 v[106:107], v[106:107], v[98:99]
	v_cvt_pk_bf16_f32 v96, v100, v101
	v_cvt_pk_bf16_f32 v97, v102, v103
	v_cvt_pk_bf16_f32 v98, v104, v105
	v_cvt_pk_bf16_f32 v99, v106, v107
	ds_bpermute_b32 v236, v238, v112
	ds_bpermute_b32 v237, v238, v113
	ds_bpermute_b32 v96, v238, v96
	ds_bpermute_b32 v97, v238, v97
	ds_bpermute_b32 v98, v238, v98
	ds_bpermute_b32 v99, v238, v99
	s_waitcnt lgkmcnt(0)
	global_store_dwordx4 v[236:237], v[96:99], off
	s_nop 0
	s_nop 0
	v_or_b32_e32 v98, 48, v144
	s_nop 0
	v_ffbh_u32_e32 v99, v193
	v_min_u32_e32 v99, 32, v99
	v_lshlrev_b64 v[96:97], v99, v[192:193]
	v_min_u32_e32 v96, 1, v96
	v_or_b32_e32 v96, v97, v96
	v_cvt_f32_u32_e32 v100, v96
	v_sub_u32_e32 v99, 32, v99
	v_mad_i64_i32 v[96:97], s[0:1], v114, s43, v[120:121]
	v_ldexp_f32 v99, v100, v99
	v_fmamk_f32 v99, v99, 0x2a000000, v158
	v_mul_f32_e32 v100, 0x4b800000, v99
	v_cmp_gt_f32_e32 vcc, s42, v99
	v_lshl_add_u64 v[96:97], v[96:97], 0, v[122:123]
	s_nop 0
	v_cndmask_b32_e32 v99, v99, v100, vcc
	v_rsq_f32_e32 v102, v99
	v_ashrrev_i32_e32 v99, 31, v98
	v_lshl_add_u64 v[100:101], v[98:99], 3, s[4:5]
	v_mul_f32_e32 v99, 0x45800000, v102
	v_cndmask_b32_e32 v99, v102, v99, vcc
	v_mul_f32_e32 v104, 0xbfb8aa3b, v99
	v_pk_mul_f32 v[84:85], v[84:85], v[104:105] op_sel_hi:[1,0]
	v_pk_mul_f32 v[86:87], v[86:87], v[104:105] op_sel_hi:[1,0]
	v_pk_mul_f32 v[80:81], v[80:81], v[104:105] op_sel_hi:[1,0]
	v_pk_mul_f32 v[82:83], v[82:83], v[104:105] op_sel_hi:[1,0]
	v_exp_f32_e32 v84, v84
	v_exp_f32_e32 v85, v85
	v_exp_f32_e32 v86, v86
	v_exp_f32_e32 v87, v87
	v_exp_f32_e32 v80, v80
	v_exp_f32_e32 v81, v81
	v_exp_f32_e32 v82, v82
	v_exp_f32_e32 v83, v83
	v_pk_add_f32 v[84:85], v[84:85], 1.0 op_sel_hi:[1,0]
	v_pk_add_f32 v[86:87], v[86:87], 1.0 op_sel_hi:[1,0]
	v_pk_add_f32 v[80:81], v[80:81], 1.0 op_sel_hi:[1,0]
	v_pk_add_f32 v[82:83], v[82:83], 1.0 op_sel_hi:[1,0]
	v_rcp_f32_e32 v84, v84
	v_rcp_f32_e32 v85, v85
	v_rcp_f32_e32 v86, v86
	v_rcp_f32_e32 v87, v87
	v_rcp_f32_e32 v80, v80
	v_rcp_f32_e32 v81, v81
	v_rcp_f32_e32 v82, v82
	v_rcp_f32_e32 v83, v83
	v_mul_f32_e32 v102, v99, v99
	v_pk_mul_f32 v[92:93], v[92:93], v[102:103] op_sel_hi:[1,0]
	v_pk_mul_f32 v[94:95], v[94:95], v[102:103] op_sel_hi:[1,0]
	v_pk_mul_f32 v[88:89], v[88:89], v[102:103] op_sel_hi:[1,0]
	v_pk_mul_f32 v[90:91], v[90:91], v[102:103] op_sel_hi:[1,0]
	v_pk_mul_f32 v[84:85], v[92:93], v[84:85]
	v_pk_mul_f32 v[86:87], v[94:95], v[86:87]
	v_pk_mul_f32 v[88:89], v[88:89], v[80:81]
	v_pk_mul_f32 v[90:91], v[90:91], v[82:83]
	v_cvt_pk_bf16_f32 v80, v84, v85
	v_cvt_pk_bf16_f32 v81, v86, v87
	v_cvt_pk_bf16_f32 v82, v88, v89
	v_cvt_pk_bf16_f32 v83, v90, v91
	ds_bpermute_b32 v236, v238, v96
	ds_bpermute_b32 v237, v238, v97
	ds_bpermute_b32 v80, v238, v80
	ds_bpermute_b32 v81, v238, v81
	ds_bpermute_b32 v82, v238, v82
	ds_bpermute_b32 v83, v238, v83
	s_waitcnt lgkmcnt(0)
	global_store_dwordx4 v[236:237], v[80:83], off
	s_nop 0
	s_nop 0
	v_ffbh_u32_e32 v82, v195
	v_min_u32_e32 v82, 32, v82
	v_lshlrev_b64 v[80:81], v82, v[194:195]
	v_min_u32_e32 v80, 1, v80
	v_or_b32_e32 v80, v81, v80
	v_cvt_f32_u32_e32 v80, v80
	v_sub_u32_e32 v81, 32, v82
	v_ldexp_f32 v80, v80, v81
	v_fmamk_f32 v80, v80, 0x2a000000, v158
	v_mul_f32_e32 v81, 0x4b800000, v80
	v_cmp_gt_f32_e32 vcc, s42, v80
	s_nop 1
	v_cndmask_b32_e32 v80, v80, v81, vcc
	v_rsq_f32_e32 v82, v80
	v_mad_i64_i32 v[80:81], s[0:1], v98, s43, v[120:121]
	v_lshl_add_u64 v[80:81], v[80:81], 0, v[122:123]
	v_mul_f32_e32 v83, 0x45800000, v82
	v_cndmask_b32_e32 v83, v82, v83, vcc
	v_mul_f32_e32 v84, 0xbfb8aa3b, v83
	v_pk_mul_f32 v[72:73], v[72:73], v[84:85] op_sel_hi:[1,0]
	v_pk_mul_f32 v[74:75], v[74:75], v[84:85] op_sel_hi:[1,0]
	v_pk_mul_f32 v[64:65], v[64:65], v[84:85] op_sel_hi:[1,0]
	v_pk_mul_f32 v[66:67], v[66:67], v[84:85] op_sel_hi:[1,0]
	v_exp_f32_e32 v72, v72
	v_exp_f32_e32 v73, v73
	v_exp_f32_e32 v74, v74
	v_exp_f32_e32 v75, v75
	v_exp_f32_e32 v64, v64
	v_exp_f32_e32 v65, v65
	v_exp_f32_e32 v66, v66
	v_exp_f32_e32 v67, v67
	v_pk_add_f32 v[72:73], v[72:73], 1.0 op_sel_hi:[1,0]
	v_pk_add_f32 v[74:75], v[74:75], 1.0 op_sel_hi:[1,0]
	v_pk_add_f32 v[64:65], v[64:65], 1.0 op_sel_hi:[1,0]
	v_pk_add_f32 v[66:67], v[66:67], 1.0 op_sel_hi:[1,0]
	v_rcp_f32_e32 v72, v72
	v_rcp_f32_e32 v73, v73
	v_rcp_f32_e32 v74, v74
	v_rcp_f32_e32 v75, v75
	v_rcp_f32_e32 v64, v64
	v_rcp_f32_e32 v65, v65
	v_rcp_f32_e32 v66, v66
	v_rcp_f32_e32 v67, v67
	v_mul_f32_e32 v82, v83, v83
	v_pk_mul_f32 v[76:77], v[76:77], v[82:83] op_sel_hi:[1,0]
	v_pk_mul_f32 v[78:79], v[78:79], v[82:83] op_sel_hi:[1,0]
	v_pk_mul_f32 v[68:69], v[68:69], v[82:83] op_sel_hi:[1,0]
	v_pk_mul_f32 v[70:71], v[70:71], v[82:83] op_sel_hi:[1,0]
	v_pk_mul_f32 v[72:73], v[76:77], v[72:73]
	v_pk_mul_f32 v[74:75], v[78:79], v[74:75]
	v_pk_mul_f32 v[68:69], v[68:69], v[64:65]
	v_pk_mul_f32 v[70:71], v[70:71], v[66:67]
	v_cvt_pk_bf16_f32 v64, v72, v73
	v_cvt_pk_bf16_f32 v65, v74, v75
	v_cvt_pk_bf16_f32 v66, v68, v69
	v_cvt_pk_bf16_f32 v67, v70, v71
	ds_bpermute_b32 v236, v238, v80
	ds_bpermute_b32 v237, v238, v81
	ds_bpermute_b32 v64, v238, v64
	ds_bpermute_b32 v65, v238, v65
	ds_bpermute_b32 v66, v238, v66
	ds_bpermute_b32 v67, v238, v67
	s_waitcnt lgkmcnt(0)
	global_store_dwordx4 v[236:237], v[64:67], off
	s_nop 0
	s_nop 0
	v_ffbh_u32_e32 v66, v197
	v_min_u32_e32 v66, 32, v66
	v_lshlrev_b64 v[64:65], v66, v[196:197]
	v_min_u32_e32 v64, 1, v64
	v_or_b32_e32 v64, v65, v64
	v_cvt_f32_u32_e32 v64, v64
	v_sub_u32_e32 v66, 32, v66
	v_add_u32_e32 v65, 0x80, v144
	v_ldexp_f32 v64, v64, v66
	v_fmamk_f32 v64, v64, 0x2a000000, v158
	v_mul_f32_e32 v66, 0x4b800000, v64
	v_cmp_gt_f32_e32 vcc, s42, v64
	s_nop 1
	v_cndmask_b32_e32 v64, v64, v66, vcc
	v_rsq_f32_e32 v66, v64
	v_mad_i64_i32 v[64:65], s[0:1], v65, s43, v[120:121]
	v_lshl_add_u64 v[64:65], v[64:65], 0, v[122:123]
	v_mul_f32_e32 v67, 0x45800000, v66
	v_cndmask_b32_e32 v67, v66, v67, vcc
	v_mul_f32_e32 v68, 0xbfb8aa3b, v67
	v_pk_mul_f32 v[52:53], v[52:53], v[68:69] op_sel_hi:[1,0]
	v_pk_mul_f32 v[54:55], v[54:55], v[68:69] op_sel_hi:[1,0]
	v_pk_mul_f32 v[48:49], v[48:49], v[68:69] op_sel_hi:[1,0]
	v_pk_mul_f32 v[50:51], v[50:51], v[68:69] op_sel_hi:[1,0]
	v_exp_f32_e32 v52, v52
	v_exp_f32_e32 v53, v53
	v_exp_f32_e32 v54, v54
	v_exp_f32_e32 v55, v55
	v_exp_f32_e32 v48, v48
	v_exp_f32_e32 v49, v49
	v_exp_f32_e32 v50, v50
	v_exp_f32_e32 v51, v51
	v_pk_add_f32 v[52:53], v[52:53], 1.0 op_sel_hi:[1,0]
	v_pk_add_f32 v[54:55], v[54:55], 1.0 op_sel_hi:[1,0]
	v_pk_add_f32 v[48:49], v[48:49], 1.0 op_sel_hi:[1,0]
	v_pk_add_f32 v[50:51], v[50:51], 1.0 op_sel_hi:[1,0]
	v_rcp_f32_e32 v52, v52
	v_rcp_f32_e32 v53, v53
	v_rcp_f32_e32 v54, v54
	v_rcp_f32_e32 v55, v55
	v_rcp_f32_e32 v48, v48
	v_rcp_f32_e32 v49, v49
	v_rcp_f32_e32 v50, v50
	v_rcp_f32_e32 v51, v51
	v_mul_f32_e32 v66, v67, v67
	v_pk_mul_f32 v[60:61], v[60:61], v[66:67] op_sel_hi:[1,0]
	v_pk_mul_f32 v[62:63], v[62:63], v[66:67] op_sel_hi:[1,0]
	v_pk_mul_f32 v[56:57], v[56:57], v[66:67] op_sel_hi:[1,0]
	v_pk_mul_f32 v[58:59], v[58:59], v[66:67] op_sel_hi:[1,0]
	v_pk_mul_f32 v[52:53], v[60:61], v[52:53]
	v_pk_mul_f32 v[54:55], v[62:63], v[54:55]
	v_pk_mul_f32 v[56:57], v[56:57], v[48:49]
	v_pk_mul_f32 v[58:59], v[58:59], v[50:51]
	v_cvt_pk_bf16_f32 v48, v52, v53
	v_cvt_pk_bf16_f32 v49, v54, v55
	v_cvt_pk_bf16_f32 v50, v56, v57
	v_cvt_pk_bf16_f32 v51, v58, v59
	ds_bpermute_b32 v236, v238, v64
	ds_bpermute_b32 v237, v238, v65
	ds_bpermute_b32 v48, v238, v48
	ds_bpermute_b32 v49, v238, v49
	ds_bpermute_b32 v50, v238, v50
	ds_bpermute_b32 v51, v238, v51
	s_waitcnt lgkmcnt(0)
	global_store_dwordx4 v[236:237], v[48:51], off
	s_nop 0
	s_nop 0
	v_ffbh_u32_e32 v50, v199
	v_min_u32_e32 v50, 32, v50
	v_lshlrev_b64 v[48:49], v50, v[198:199]
	v_min_u32_e32 v48, 1, v48
	v_or_b32_e32 v48, v49, v48
	v_cvt_f32_u32_e32 v48, v48
	v_sub_u32_e32 v50, 32, v50
	v_add_u32_e32 v49, 0x90, v144
	v_ldexp_f32 v48, v48, v50
	v_fmamk_f32 v48, v48, 0x2a000000, v158
	v_mul_f32_e32 v50, 0x4b800000, v48
	v_cmp_gt_f32_e32 vcc, s42, v48
	s_nop 1
	v_cndmask_b32_e32 v48, v48, v50, vcc
	v_rsq_f32_e32 v50, v48
	v_mad_i64_i32 v[48:49], s[0:1], v49, s43, v[120:121]
	v_lshl_add_u64 v[48:49], v[48:49], 0, v[122:123]
	v_mul_f32_e32 v51, 0x45800000, v50
	v_cndmask_b32_e32 v51, v50, v51, vcc
	v_mul_f32_e32 v52, 0xbfb8aa3b, v51
	v_pk_mul_f32 v[36:37], v[36:37], v[52:53] op_sel_hi:[1,0]
	v_pk_mul_f32 v[38:39], v[38:39], v[52:53] op_sel_hi:[1,0]
	v_pk_mul_f32 v[32:33], v[32:33], v[52:53] op_sel_hi:[1,0]
	v_pk_mul_f32 v[34:35], v[34:35], v[52:53] op_sel_hi:[1,0]
	v_exp_f32_e32 v36, v36
	v_exp_f32_e32 v37, v37
	v_exp_f32_e32 v38, v38
	v_exp_f32_e32 v39, v39
	v_exp_f32_e32 v32, v32
	v_exp_f32_e32 v33, v33
	v_exp_f32_e32 v34, v34
	v_exp_f32_e32 v35, v35
	v_pk_add_f32 v[36:37], v[36:37], 1.0 op_sel_hi:[1,0]
	v_pk_add_f32 v[38:39], v[38:39], 1.0 op_sel_hi:[1,0]
	v_pk_add_f32 v[32:33], v[32:33], 1.0 op_sel_hi:[1,0]
	v_pk_add_f32 v[34:35], v[34:35], 1.0 op_sel_hi:[1,0]
	v_rcp_f32_e32 v36, v36
	v_rcp_f32_e32 v37, v37
	v_rcp_f32_e32 v38, v38
	v_rcp_f32_e32 v39, v39
	v_rcp_f32_e32 v32, v32
	v_rcp_f32_e32 v33, v33
	v_rcp_f32_e32 v34, v34
	v_rcp_f32_e32 v35, v35
	v_mul_f32_e32 v50, v51, v51
	v_pk_mul_f32 v[44:45], v[44:45], v[50:51] op_sel_hi:[1,0]
	v_pk_mul_f32 v[46:47], v[46:47], v[50:51] op_sel_hi:[1,0]
	v_pk_mul_f32 v[40:41], v[40:41], v[50:51] op_sel_hi:[1,0]
	v_pk_mul_f32 v[42:43], v[42:43], v[50:51] op_sel_hi:[1,0]
	v_pk_mul_f32 v[36:37], v[44:45], v[36:37]
	v_pk_mul_f32 v[38:39], v[46:47], v[38:39]
	v_pk_mul_f32 v[40:41], v[40:41], v[32:33]
	v_pk_mul_f32 v[42:43], v[42:43], v[34:35]
	v_cvt_pk_bf16_f32 v32, v36, v37
	v_cvt_pk_bf16_f32 v33, v38, v39
	v_cvt_pk_bf16_f32 v34, v40, v41
	v_cvt_pk_bf16_f32 v35, v42, v43
	ds_bpermute_b32 v236, v238, v48
	ds_bpermute_b32 v237, v238, v49
	ds_bpermute_b32 v32, v238, v32
	ds_bpermute_b32 v33, v238, v33
	ds_bpermute_b32 v34, v238, v34
	ds_bpermute_b32 v35, v238, v35
	s_waitcnt lgkmcnt(0)
	global_store_dwordx4 v[236:237], v[32:35], off
	s_nop 0
	s_nop 0
	v_ffbh_u32_e32 v34, v201
	v_min_u32_e32 v34, 32, v34
	v_lshlrev_b64 v[32:33], v34, v[200:201]
	v_min_u32_e32 v32, 1, v32
	v_or_b32_e32 v32, v33, v32
	v_cvt_f32_u32_e32 v32, v32
	v_sub_u32_e32 v34, 32, v34
	v_add_u32_e32 v33, 0xa0, v144
	v_ldexp_f32 v32, v32, v34
	v_fmamk_f32 v32, v32, 0x2a000000, v158
	v_mul_f32_e32 v34, 0x4b800000, v32
	v_cmp_gt_f32_e32 vcc, s42, v32
	s_nop 1
	v_cndmask_b32_e32 v32, v32, v34, vcc
	v_rsq_f32_e32 v34, v32
	v_mad_i64_i32 v[32:33], s[0:1], v33, s43, v[120:121]
	v_lshl_add_u64 v[32:33], v[32:33], 0, v[122:123]
	v_mul_f32_e32 v35, 0x45800000, v34
	v_cndmask_b32_e32 v35, v34, v35, vcc
	v_mul_f32_e32 v36, 0xbfb8aa3b, v35
	v_pk_mul_f32 v[20:21], v[20:21], v[36:37] op_sel_hi:[1,0]
	v_pk_mul_f32 v[22:23], v[22:23], v[36:37] op_sel_hi:[1,0]
	v_pk_mul_f32 v[16:17], v[16:17], v[36:37] op_sel_hi:[1,0]
	v_pk_mul_f32 v[18:19], v[18:19], v[36:37] op_sel_hi:[1,0]
	v_exp_f32_e32 v20, v20
	v_exp_f32_e32 v21, v21
	v_exp_f32_e32 v22, v22
	v_exp_f32_e32 v23, v23
	v_exp_f32_e32 v16, v16
	v_exp_f32_e32 v17, v17
	v_exp_f32_e32 v18, v18
	v_exp_f32_e32 v19, v19
	v_pk_add_f32 v[20:21], v[20:21], 1.0 op_sel_hi:[1,0]
	v_pk_add_f32 v[22:23], v[22:23], 1.0 op_sel_hi:[1,0]
	v_pk_add_f32 v[16:17], v[16:17], 1.0 op_sel_hi:[1,0]
	v_pk_add_f32 v[18:19], v[18:19], 1.0 op_sel_hi:[1,0]
	v_rcp_f32_e32 v20, v20
	v_rcp_f32_e32 v21, v21
	v_rcp_f32_e32 v22, v22
	v_rcp_f32_e32 v23, v23
	v_rcp_f32_e32 v16, v16
	v_rcp_f32_e32 v17, v17
	v_rcp_f32_e32 v18, v18
	v_rcp_f32_e32 v19, v19
	v_mul_f32_e32 v34, v35, v35
	v_pk_mul_f32 v[28:29], v[28:29], v[34:35] op_sel_hi:[1,0]
	v_pk_mul_f32 v[30:31], v[30:31], v[34:35] op_sel_hi:[1,0]
	v_pk_mul_f32 v[24:25], v[24:25], v[34:35] op_sel_hi:[1,0]
	v_pk_mul_f32 v[26:27], v[26:27], v[34:35] op_sel_hi:[1,0]
	v_pk_mul_f32 v[20:21], v[28:29], v[20:21]
	v_pk_mul_f32 v[22:23], v[30:31], v[22:23]
	v_pk_mul_f32 v[24:25], v[24:25], v[16:17]
	v_pk_mul_f32 v[26:27], v[26:27], v[18:19]
	v_cvt_pk_bf16_f32 v16, v20, v21
	v_cvt_pk_bf16_f32 v17, v22, v23
	v_cvt_pk_bf16_f32 v18, v24, v25
	v_cvt_pk_bf16_f32 v19, v26, v27
	ds_bpermute_b32 v236, v238, v32
	ds_bpermute_b32 v237, v238, v33
	ds_bpermute_b32 v16, v238, v16
	ds_bpermute_b32 v17, v238, v17
	ds_bpermute_b32 v18, v238, v18
	ds_bpermute_b32 v19, v238, v19
	s_waitcnt lgkmcnt(0)
	global_store_dwordx4 v[236:237], v[16:19], off
	s_nop 0
	s_andn2_b64 vcc, exec, s[6:7]
	s_nop 0
	v_ffbh_u32_e32 v18, v203
	v_min_u32_e32 v18, 32, v18
	v_lshlrev_b64 v[16:17], v18, v[202:203]
	v_min_u32_e32 v16, 1, v16
	v_or_b32_e32 v16, v17, v16
	v_cvt_f32_u32_e32 v16, v16
	v_sub_u32_e32 v18, 32, v18
	v_add_u32_e32 v17, 0xb0, v144
	v_ldexp_f32 v16, v16, v18
	v_fmamk_f32 v16, v16, 0x2a000000, v158
	v_mul_f32_e32 v18, 0x4b800000, v16
	v_cmp_gt_f32_e64 s[0:1], s42, v16
	s_nop 1
	v_cndmask_b32_e64 v16, v16, v18, s[0:1]
	v_rsq_f32_e32 v18, v16
	v_mad_i64_i32 v[16:17], s[20:21], v17, s43, v[120:121]
	v_lshl_add_u64 v[16:17], v[16:17], 0, v[122:123]
	v_mul_f32_e32 v19, 0x45800000, v18
	v_cndmask_b32_e64 v19, v18, v19, s[0:1]
	v_mul_f32_e32 v20, 0xbfb8aa3b, v19
	v_pk_mul_f32 v[4:5], v[4:5], v[20:21] op_sel_hi:[1,0]
	v_pk_mul_f32 v[6:7], v[6:7], v[20:21] op_sel_hi:[1,0]
	v_pk_mul_f32 v[0:1], v[0:1], v[20:21] op_sel_hi:[1,0]
	v_pk_mul_f32 v[2:3], v[2:3], v[20:21] op_sel_hi:[1,0]
	v_exp_f32_e32 v4, v4
	v_exp_f32_e32 v5, v5
	v_exp_f32_e32 v6, v6
	v_exp_f32_e32 v7, v7
	v_exp_f32_e32 v0, v0
	v_exp_f32_e32 v1, v1
	v_exp_f32_e32 v2, v2
	v_exp_f32_e32 v3, v3
	v_pk_add_f32 v[4:5], v[4:5], 1.0 op_sel_hi:[1,0]
	v_pk_add_f32 v[6:7], v[6:7], 1.0 op_sel_hi:[1,0]
	v_pk_add_f32 v[0:1], v[0:1], 1.0 op_sel_hi:[1,0]
	v_pk_add_f32 v[2:3], v[2:3], 1.0 op_sel_hi:[1,0]
	v_rcp_f32_e32 v4, v4
	v_rcp_f32_e32 v5, v5
	v_rcp_f32_e32 v6, v6
	v_rcp_f32_e32 v7, v7
	v_rcp_f32_e32 v0, v0
	v_rcp_f32_e32 v1, v1
	v_rcp_f32_e32 v2, v2
	v_rcp_f32_e32 v3, v3
	v_mul_f32_e32 v18, v19, v19
	v_pk_mul_f32 v[12:13], v[12:13], v[18:19] op_sel_hi:[1,0]
	v_pk_mul_f32 v[14:15], v[14:15], v[18:19] op_sel_hi:[1,0]
	v_pk_mul_f32 v[8:9], v[8:9], v[18:19] op_sel_hi:[1,0]
	v_pk_mul_f32 v[10:11], v[10:11], v[18:19] op_sel_hi:[1,0]
	v_pk_mul_f32 v[4:5], v[12:13], v[4:5]
	v_pk_mul_f32 v[6:7], v[14:15], v[6:7]
	v_pk_mul_f32 v[8:9], v[8:9], v[0:1]
	v_pk_mul_f32 v[10:11], v[10:11], v[2:3]
	v_cvt_pk_bf16_f32 v0, v4, v5
	v_cvt_pk_bf16_f32 v1, v6, v7
	v_cvt_pk_bf16_f32 v2, v8, v9
	v_cvt_pk_bf16_f32 v3, v10, v11
	s_mov_b64 s[0:1], -1
	ds_bpermute_b32 v236, v238, v16
	ds_bpermute_b32 v237, v238, v17
	ds_bpermute_b32 v0, v238, v0
	ds_bpermute_b32 v1, v238, v1
	ds_bpermute_b32 v2, v238, v2
	ds_bpermute_b32 v3, v238, v3
	s_waitcnt lgkmcnt(0)
	global_store_dwordx4 v[236:237], v[0:3], off
	s_cbranch_vccnz .LBB0_2303
	s_andn2_b64 vcc, exec, s[2:3]
	s_cbranch_vccnz .LBB0_2302
	s_barrier
	s_branch .LBB0_2302
